# LayerNorm pass (both MODE-1 copies): hand-written loop body, ~25% fewer VALU instructions per row; (x-mu)*rstd evaluated as fma(x, rstd, -mu*rstd), all f32
# speedup vs baseline: 1.0031x; 1.0031x over previous
.LBB0_216:
	s_or_b64 exec, exec, s[34:35]
	s_and_b64 s[0:1], exec, vcc
	s_or_b64 s[20:21], s[0:1], s[20:21]
	s_nop 1
	v_mov_b32_e32 v140, s99
	v_fma_f32 v141, -v140, v140, s98
	v_max_f32_e32 v141, 0, v141
	v_add_f32_e32 v141, 0x358637bd, v141
	v_mul_f32_e32 v142, 0x4b800000, v141
	v_cmp_gt_f32_e64 s[42:43], s58, v141
	s_nop 1
	v_cndmask_b32_e64 v141, v141, v142, s[42:43]
	v_rsq_f32_e32 v141, v141
	s_nop 0
	v_mul_f32_e32 v142, 0x45800000, v141
	v_cndmask_b32_e64 v141, v141, v142, s[42:43]
	v_mul_f32_e64 v139, -v140, v141
	s_waitcnt vmcnt(0)
	v_fma_f32 v121, v121, v141, v139
	v_fma_f32 v122, v122, v141, v139
	v_fma_f32 v123, v123, v141, v139
	v_fma_f32 v124, v124, v141, v139
	v_fma_f32 v125, v125, v141, v139
	v_fma_f32 v126, v126, v141, v139
	v_fma_f32 v127, v127, v141, v139
	v_fma_f32 v128, v128, v141, v139
	v_fma_f32 v129, v129, v141, v139
	v_fma_f32 v130, v130, v141, v139
	v_fma_f32 v131, v131, v141, v139
	v_fma_f32 v132, v132, v141, v139
	v_fma_f32 v133, v133, v141, v139
	v_fma_f32 v134, v134, v141, v139
	v_fma_f32 v135, v135, v141, v139
	v_fma_f32 v136, v136, v141, v139
	v_fma_f32 v121, v121, v54, v46
	v_fma_f32 v122, v122, v55, v47
	v_fma_f32 v123, v123, v56, v48
	v_fma_f32 v124, v124, v57, v49
	v_fma_f32 v125, v125, v58, v42
	v_fma_f32 v126, v126, v59, v43
	v_fma_f32 v127, v127, v60, v44
	v_fma_f32 v128, v128, v61, v45
	v_fma_f32 v129, v129, v66, v62
	v_fma_f32 v130, v130, v67, v63
	v_fma_f32 v131, v131, v68, v64
	v_fma_f32 v132, v132, v69, v65
	v_fma_f32 v133, v133, v70, v50
	v_fma_f32 v134, v134, v71, v51
	v_fma_f32 v135, v135, v72, v52
	v_fma_f32 v136, v136, v73, v53
	s_mov_b32 s0, 0x5000000
	s_mov_b32 s1, 0
	v_lshl_add_u64 v[152:153], v[92:93], 0, s[0:1]
	v_cvt_pk_bf16_f32 v144, v121, v122
	v_cvt_pk_bf16_f32 v145, v123, v124
	v_cvt_pk_bf16_f32 v146, v125, v126
	v_cvt_pk_bf16_f32 v147, v127, v128
	global_store_dwordx4 v[152:153], v[144:147], off
	v_cvt_pk_bf16_f32 v148, v129, v130
	v_cvt_pk_bf16_f32 v149, v131, v132
	v_cvt_pk_bf16_f32 v150, v133, v134
	v_cvt_pk_bf16_f32 v151, v135, v136
	global_store_dwordx4 v[152:153], v[148:151], off offset:1024
	s_mov_b64 s[0:1], 0x800
	v_lshl_add_u64 v[88:89], v[88:89], 0, 8
	v_lshl_add_u64 v[90:91], v[90:91], 0, s[0:1]
	v_mov_b64_e32 v[80:81], v[36:37]
	v_mov_b64_e32 v[76:77], v[40:41]
	v_mov_b64_e32 v[74:75], v[38:39]
	v_mov_b64_e32 v[78:79], v[34:35]
	v_mov_b32_e32 v119, v83
	s_andn2_b64 exec, exec, s[20:21]
	s_cbranch_execz .LBB0_223

.LBB0_219:
	s_or_b64 exec, exec, s[34:35]
	v_lshlrev_b32_e32 v121, 16, v78
	v_and_b32_e32 v122, 0xffff0000, v78
	v_lshlrev_b32_e32 v123, 16, v79
	v_and_b32_e32 v124, 0xffff0000, v79
	v_lshlrev_b32_e32 v125, 16, v80
	v_and_b32_e32 v126, 0xffff0000, v80
	v_lshlrev_b32_e32 v127, 16, v81
	v_and_b32_e32 v128, 0xffff0000, v81
	v_lshlrev_b32_e32 v129, 16, v74
	v_and_b32_e32 v130, 0xffff0000, v74
	v_lshlrev_b32_e32 v131, 16, v75
	v_and_b32_e32 v132, 0xffff0000, v75
	v_lshlrev_b32_e32 v133, 16, v76
	v_and_b32_e32 v134, 0xffff0000, v76
	v_lshlrev_b32_e32 v135, 16, v77
	v_and_b32_e32 v136, 0xffff0000, v77
	v_add_f32_e32 v137, v121, v122
	v_mul_f32_e32 v138, v121, v121
	v_fmac_f32_e32 v138, v122, v122
	v_add_f32_e32 v137, v137, v123
	v_fmac_f32_e32 v138, v123, v123
	v_add_f32_e32 v137, v137, v124
	v_fmac_f32_e32 v138, v124, v124
	v_add_f32_e32 v137, v137, v125
	v_fmac_f32_e32 v138, v125, v125
	v_add_f32_e32 v137, v137, v126
	v_fmac_f32_e32 v138, v126, v126
	v_add_f32_e32 v137, v137, v127
	v_fmac_f32_e32 v138, v127, v127
	v_add_f32_e32 v137, v137, v128
	v_fmac_f32_e32 v138, v128, v128
	v_add_f32_e32 v137, v137, v129
	v_fmac_f32_e32 v138, v129, v129
	v_add_f32_e32 v137, v137, v130
	v_fmac_f32_e32 v138, v130, v130
	v_add_f32_e32 v137, v137, v131
	v_fmac_f32_e32 v138, v131, v131
	v_add_f32_e32 v137, v137, v132
	v_fmac_f32_e32 v138, v132, v132
	v_add_f32_e32 v137, v137, v133
	v_fmac_f32_e32 v138, v133, v133
	v_add_f32_e32 v137, v137, v134
	v_fmac_f32_e32 v138, v134, v134
	v_add_f32_e32 v137, v137, v135
	v_fmac_f32_e32 v138, v135, v135
	v_add_f32_e32 v137, v137, v136
	v_fmac_f32_e32 v138, v136, v136
	s_nop 1
	v_add_f32_dpp v138, v138, v138 quad_perm:[1,0,3,2] row_mask:0xf bank_mask:0xf
	v_add_f32_dpp v137, v137, v137 quad_perm:[1,0,3,2] row_mask:0xf bank_mask:0xf
	s_nop 0
	v_add_f32_dpp v138, v138, v138 quad_perm:[2,3,0,1] row_mask:0xf bank_mask:0xf
	v_add_f32_dpp v137, v137, v137 quad_perm:[2,3,0,1] row_mask:0xf bank_mask:0xf
	s_nop 0
	v_add_f32_dpp v138, v138, v138 row_half_mirror row_mask:0xf bank_mask:0xf
	v_add_f32_dpp v137, v137, v137 row_half_mirror row_mask:0xf bank_mask:0xf
	s_nop 0
	v_add_f32_dpp v138, v138, v138 row_mirror row_mask:0xf bank_mask:0xf
	v_add_f32_dpp v137, v137, v137 row_mirror row_mask:0xf bank_mask:0xf
	s_nop 0
	v_add_f32_dpp v138, v138, v138 row_bcast:15 row_mask:0xa bank_mask:0xf
	v_add_f32_dpp v137, v137, v137 row_bcast:15 row_mask:0xa bank_mask:0xf
	s_nop 0
	v_add_f32_dpp v138, v138, v138 row_bcast:31 row_mask:0xc bank_mask:0xf
	v_add_f32_dpp v137, v137, v137 row_bcast:31 row_mask:0xc bank_mask:0xf
	s_nop 0
	s_mov_b32 s0, 0x3a800000
	v_mul_f32_e32 v138, s0, v138
	v_mul_f32_e32 v137, s0, v137
	s_nop 0
	v_readlane_b32 s98, v138, 63
	v_readlane_b32 s99, v137, 63
	s_nop 1
	v_mov_b32_e32 v140, s99
	v_fma_f32 v141, -v140, v140, s98
	v_max_f32_e32 v141, 0, v141
	v_add_f32_e32 v141, 0x358637bd, v141
	v_mul_f32_e32 v142, 0x4b800000, v141
	v_cmp_gt_f32_e64 s[42:43], s58, v141
	s_nop 1
	v_cndmask_b32_e64 v141, v141, v142, s[42:43]
	v_rsq_f32_e32 v141, v141
	s_nop 0
	v_mul_f32_e32 v142, 0x45800000, v141
	v_cndmask_b32_e64 v141, v141, v142, s[42:43]
	v_mul_f32_e64 v139, -v140, v141
	s_and_saveexec_b64 s[34:35], s[40:41]
	s_cbranch_execz .LBB0_221
	v_lshl_add_u64 v[154:155], s[12:13], 0, v[88:89]
	global_store_dwordx2 v[154:155], v[140:141], off
.LBB0_221:
	s_or_b64 exec, exec, s[34:35]
	v_fma_f32 v121, v121, v141, v139
	v_fma_f32 v122, v122, v141, v139
	v_fma_f32 v123, v123, v141, v139
	v_fma_f32 v124, v124, v141, v139
	v_fma_f32 v125, v125, v141, v139
	v_fma_f32 v126, v126, v141, v139
	v_fma_f32 v127, v127, v141, v139
	v_fma_f32 v128, v128, v141, v139
	v_fma_f32 v129, v129, v141, v139
	v_fma_f32 v130, v130, v141, v139
	v_fma_f32 v131, v131, v141, v139
	v_fma_f32 v132, v132, v141, v139
	v_fma_f32 v133, v133, v141, v139
	v_fma_f32 v134, v134, v141, v139
	v_fma_f32 v135, v135, v141, v139
	v_fma_f32 v136, v136, v141, v139
	v_fma_f32 v121, v6, v121, v14
	v_fma_f32 v122, v7, v122, v15
	v_fma_f32 v123, v8, v123, v16
	v_fma_f32 v124, v9, v124, v17
	v_fma_f32 v125, v2, v125, v10
	v_fma_f32 v126, v3, v126, v11
	v_fma_f32 v127, v4, v127, v12
	v_fma_f32 v128, v5, v128, v13
	v_fma_f32 v129, v22, v129, v30
	v_fma_f32 v130, v23, v130, v31
	v_fma_f32 v131, v24, v131, v32
	v_fma_f32 v132, v25, v132, v33
	v_fma_f32 v133, v18, v133, v26
	v_fma_f32 v134, v19, v134, v27
	v_fma_f32 v135, v20, v135, v28
	v_fma_f32 v136, v21, v136, v29
	v_add_f32_e32 v137, v121, v122
	v_mul_f32_e32 v138, v121, v121
	v_fmac_f32_e32 v138, v122, v122
	v_add_f32_e32 v137, v137, v123
	v_fmac_f32_e32 v138, v123, v123
	v_add_f32_e32 v137, v137, v124
	v_fmac_f32_e32 v138, v124, v124
	v_add_f32_e32 v137, v137, v125
	v_fmac_f32_e32 v138, v125, v125
	v_add_f32_e32 v137, v137, v126
	v_fmac_f32_e32 v138, v126, v126
	v_add_f32_e32 v137, v137, v127
	v_fmac_f32_e32 v138, v127, v127
	v_add_f32_e32 v137, v137, v128
	v_fmac_f32_e32 v138, v128, v128
	v_add_f32_e32 v137, v137, v129
	v_fmac_f32_e32 v138, v129, v129
	v_add_f32_e32 v137, v137, v130
	v_fmac_f32_e32 v138, v130, v130
	v_add_f32_e32 v137, v137, v131
	v_fmac_f32_e32 v138, v131, v131
	v_add_f32_e32 v137, v137, v132
	v_fmac_f32_e32 v138, v132, v132
	v_add_f32_e32 v137, v137, v133
	v_fmac_f32_e32 v138, v133, v133
	v_add_f32_e32 v137, v137, v134
	v_fmac_f32_e32 v138, v134, v134
	v_add_f32_e32 v137, v137, v135
	v_fmac_f32_e32 v138, v135, v135
	v_add_f32_e32 v137, v137, v136
	v_fmac_f32_e32 v138, v136, v136
	s_nop 1
	v_add_f32_dpp v138, v138, v138 quad_perm:[1,0,3,2] row_mask:0xf bank_mask:0xf
	v_add_f32_dpp v137, v137, v137 quad_perm:[1,0,3,2] row_mask:0xf bank_mask:0xf
	s_nop 0
	v_add_f32_dpp v138, v138, v138 quad_perm:[2,3,0,1] row_mask:0xf bank_mask:0xf
	v_add_f32_dpp v137, v137, v137 quad_perm:[2,3,0,1] row_mask:0xf bank_mask:0xf
	s_nop 0
	v_add_f32_dpp v138, v138, v138 row_half_mirror row_mask:0xf bank_mask:0xf
	v_add_f32_dpp v137, v137, v137 row_half_mirror row_mask:0xf bank_mask:0xf
	s_nop 0
	v_add_f32_dpp v138, v138, v138 row_mirror row_mask:0xf bank_mask:0xf
	v_add_f32_dpp v137, v137, v137 row_mirror row_mask:0xf bank_mask:0xf
	s_nop 0
	v_add_f32_dpp v138, v138, v138 row_bcast:15 row_mask:0xa bank_mask:0xf
	v_add_f32_dpp v137, v137, v137 row_bcast:15 row_mask:0xa bank_mask:0xf
	s_nop 0
	v_add_f32_dpp v138, v138, v138 row_bcast:31 row_mask:0xc bank_mask:0xf
	v_add_f32_dpp v137, v137, v137 row_bcast:31 row_mask:0xc bank_mask:0xf
	s_nop 0
	s_mov_b32 s0, 0x3a800000
	v_mul_f32_e32 v138, s0, v138
	v_mul_f32_e32 v137, s0, v137
	s_nop 0
	v_readlane_b32 s98, v138, 63
	v_readlane_b32 s99, v137, 63
	v_add_u32_e32 v0, 0xfffff000, v119
	v_lshrrev_b32_e32 v0, 11, v0
	v_add_u32_e32 v0, 1, v0
	v_cmp_lt_i32_e64 s[42:43], s29, v119
	v_cndmask_b32_e64 v106, 0, v0, s[42:43]
	v_cmp_ne_u32_e64 s[42:43], v106, v118
	s_and_saveexec_b64 s[34:35], s[42:43]
	s_cbranch_execz .LBB0_216
	v_mul_u32_u24_e32 v0, 0x1800, v106
	v_lshlrev_b64 v[42:43], 2, v[0:1]
	v_lshl_add_u64 v[44:45], v[84:85], 0, v[42:43]
	v_lshl_add_u64 v[62:63], v[86:87], 0, v[42:43]
	global_load_dwordx4 v[54:57], v[44:45], off
	global_load_dwordx4 v[58:61], v[44:45], off offset:16
	global_load_dwordx4 v[70:73], v[44:45], off offset:2064
	global_load_dwordx4 v[66:69], v[44:45], off offset:2048
	s_nop 0
	global_load_dwordx4 v[42:45], v[62:63], off offset:16
	global_load_dwordx4 v[46:49], v[62:63], off
	global_load_dwordx4 v[50:53], v[62:63], off offset:2064
	s_nop 0
	global_load_dwordx4 v[62:65], v[62:63], off offset:2048
	v_mov_b32_e32 v118, v106
	s_waitcnt vmcnt(7)
	v_add_f32_e32 v56, 1.0, v56
	v_add_f32_e32 v57, 1.0, v57
	v_add_f32_e32 v54, 1.0, v54
	v_add_f32_e32 v55, 1.0, v55
	s_waitcnt vmcnt(6)
	v_add_f32_e32 v60, 1.0, v60
	v_add_f32_e32 v61, 1.0, v61
	v_add_f32_e32 v58, 1.0, v58
	v_add_f32_e32 v59, 1.0, v59
	s_waitcnt vmcnt(4)
	v_add_f32_e32 v68, 1.0, v68
	v_add_f32_e32 v69, 1.0, v69
	v_add_f32_e32 v66, 1.0, v66
	v_add_f32_e32 v67, 1.0, v67
	v_add_f32_e32 v72, 1.0, v72
	v_add_f32_e32 v73, 1.0, v73
	v_add_f32_e32 v70, 1.0, v70
	v_add_f32_e32 v71, 1.0, v71
	s_branch .LBB0_216

.LBB0_760:
	s_or_b64 exec, exec, s[16:17]
	s_and_b64 s[0:1], exec, vcc
	s_or_b64 s[14:15], s[0:1], s[14:15]
	s_nop 1
	v_mov_b32_e32 v140, s99
	v_fma_f32 v141, -v140, v140, s98
	v_max_f32_e32 v141, 0, v141
	v_add_f32_e32 v141, 0x358637bd, v141
	v_mul_f32_e32 v142, 0x4b800000, v141
	v_cmp_gt_f32_e64 s[42:43], s58, v141
	s_nop 1
	v_cndmask_b32_e64 v141, v141, v142, s[42:43]
	v_rsq_f32_e32 v141, v141
	s_nop 0
	v_mul_f32_e32 v142, 0x45800000, v141
	v_cndmask_b32_e64 v141, v141, v142, s[42:43]
	v_mul_f32_e64 v139, -v140, v141
	s_waitcnt vmcnt(0)
	v_fma_f32 v121, v121, v141, v139
	v_fma_f32 v122, v122, v141, v139
	v_fma_f32 v123, v123, v141, v139
	v_fma_f32 v124, v124, v141, v139
	v_fma_f32 v125, v125, v141, v139
	v_fma_f32 v126, v126, v141, v139
	v_fma_f32 v127, v127, v141, v139
	v_fma_f32 v128, v128, v141, v139
	v_fma_f32 v129, v129, v141, v139
	v_fma_f32 v130, v130, v141, v139
	v_fma_f32 v131, v131, v141, v139
	v_fma_f32 v132, v132, v141, v139
	v_fma_f32 v133, v133, v141, v139
	v_fma_f32 v134, v134, v141, v139
	v_fma_f32 v135, v135, v141, v139
	v_fma_f32 v136, v136, v141, v139
	v_fma_f32 v121, v121, v54, v46
	v_fma_f32 v122, v122, v55, v47
	v_fma_f32 v123, v123, v56, v48
	v_fma_f32 v124, v124, v57, v49
	v_fma_f32 v125, v125, v58, v42
	v_fma_f32 v126, v126, v59, v43
	v_fma_f32 v127, v127, v60, v44
	v_fma_f32 v128, v128, v61, v45
	v_fma_f32 v129, v129, v66, v62
	v_fma_f32 v130, v130, v67, v63
	v_fma_f32 v131, v131, v68, v64
	v_fma_f32 v132, v132, v69, v65
	v_fma_f32 v133, v133, v70, v50
	v_fma_f32 v134, v134, v71, v51
	v_fma_f32 v135, v135, v72, v52
	v_fma_f32 v136, v136, v73, v53
	s_mov_b32 s0, 0xbe00000
	s_mov_b32 s1, 0
	v_lshl_add_u64 v[152:153], v[90:91], 0, s[0:1]
	v_cvt_pk_bf16_f32 v144, v121, v122
	v_cvt_pk_bf16_f32 v145, v123, v124
	v_cvt_pk_bf16_f32 v146, v125, v126
	v_cvt_pk_bf16_f32 v147, v127, v128
	global_store_dwordx4 v[152:153], v[144:147], off
	v_cvt_pk_bf16_f32 v148, v129, v130
	v_cvt_pk_bf16_f32 v149, v131, v132
	v_cvt_pk_bf16_f32 v150, v133, v134
	v_cvt_pk_bf16_f32 v151, v135, v136
	global_store_dwordx4 v[152:153], v[148:151], off offset:1024
	s_mov_b64 s[0:1], 0x800
	v_lshl_add_u64 v[86:87], v[86:87], 0, 8
	v_lshl_add_u64 v[88:89], v[88:89], 0, s[0:1]
	v_mov_b64_e32 v[80:81], v[36:37]
	v_mov_b64_e32 v[76:77], v[40:41]
	v_mov_b64_e32 v[74:75], v[38:39]
	v_mov_b64_e32 v[78:79], v[34:35]
	v_mov_b32_e32 v92, v93
	s_andn2_b64 exec, exec, s[14:15]
	s_cbranch_execz .LBB0_767

.LBB0_763:
	s_or_b64 exec, exec, s[16:17]
	v_lshlrev_b32_e32 v121, 16, v78
	v_and_b32_e32 v122, 0xffff0000, v78
	v_lshlrev_b32_e32 v123, 16, v79
	v_and_b32_e32 v124, 0xffff0000, v79
	v_lshlrev_b32_e32 v125, 16, v80
	v_and_b32_e32 v126, 0xffff0000, v80
	v_lshlrev_b32_e32 v127, 16, v81
	v_and_b32_e32 v128, 0xffff0000, v81
	v_lshlrev_b32_e32 v129, 16, v74
	v_and_b32_e32 v130, 0xffff0000, v74
	v_lshlrev_b32_e32 v131, 16, v75
	v_and_b32_e32 v132, 0xffff0000, v75
	v_lshlrev_b32_e32 v133, 16, v76
	v_and_b32_e32 v134, 0xffff0000, v76
	v_lshlrev_b32_e32 v135, 16, v77
	v_and_b32_e32 v136, 0xffff0000, v77
	v_add_f32_e32 v137, v121, v122
	v_mul_f32_e32 v138, v121, v121
	v_fmac_f32_e32 v138, v122, v122
	v_add_f32_e32 v137, v137, v123
	v_fmac_f32_e32 v138, v123, v123
	v_add_f32_e32 v137, v137, v124
	v_fmac_f32_e32 v138, v124, v124
	v_add_f32_e32 v137, v137, v125
	v_fmac_f32_e32 v138, v125, v125
	v_add_f32_e32 v137, v137, v126
	v_fmac_f32_e32 v138, v126, v126
	v_add_f32_e32 v137, v137, v127
	v_fmac_f32_e32 v138, v127, v127
	v_add_f32_e32 v137, v137, v128
	v_fmac_f32_e32 v138, v128, v128
	v_add_f32_e32 v137, v137, v129
	v_fmac_f32_e32 v138, v129, v129
	v_add_f32_e32 v137, v137, v130
	v_fmac_f32_e32 v138, v130, v130
	v_add_f32_e32 v137, v137, v131
	v_fmac_f32_e32 v138, v131, v131
	v_add_f32_e32 v137, v137, v132
	v_fmac_f32_e32 v138, v132, v132
	v_add_f32_e32 v137, v137, v133
	v_fmac_f32_e32 v138, v133, v133
	v_add_f32_e32 v137, v137, v134
	v_fmac_f32_e32 v138, v134, v134
	v_add_f32_e32 v137, v137, v135
	v_fmac_f32_e32 v138, v135, v135
	v_add_f32_e32 v137, v137, v136
	v_fmac_f32_e32 v138, v136, v136
	s_nop 1
	v_add_f32_dpp v138, v138, v138 quad_perm:[1,0,3,2] row_mask:0xf bank_mask:0xf
	v_add_f32_dpp v137, v137, v137 quad_perm:[1,0,3,2] row_mask:0xf bank_mask:0xf
	s_nop 0
	v_add_f32_dpp v138, v138, v138 quad_perm:[2,3,0,1] row_mask:0xf bank_mask:0xf
	v_add_f32_dpp v137, v137, v137 quad_perm:[2,3,0,1] row_mask:0xf bank_mask:0xf
	s_nop 0
	v_add_f32_dpp v138, v138, v138 row_half_mirror row_mask:0xf bank_mask:0xf
	v_add_f32_dpp v137, v137, v137 row_half_mirror row_mask:0xf bank_mask:0xf
	s_nop 0
	v_add_f32_dpp v138, v138, v138 row_mirror row_mask:0xf bank_mask:0xf
	v_add_f32_dpp v137, v137, v137 row_mirror row_mask:0xf bank_mask:0xf
	s_nop 0
	v_add_f32_dpp v138, v138, v138 row_bcast:15 row_mask:0xa bank_mask:0xf
	v_add_f32_dpp v137, v137, v137 row_bcast:15 row_mask:0xa bank_mask:0xf
	s_nop 0
	v_add_f32_dpp v138, v138, v138 row_bcast:31 row_mask:0xc bank_mask:0xf
	v_add_f32_dpp v137, v137, v137 row_bcast:31 row_mask:0xc bank_mask:0xf
	s_nop 0
	s_mov_b32 s0, 0x3a800000
	v_mul_f32_e32 v138, s0, v138
	v_mul_f32_e32 v137, s0, v137
	s_nop 0
	v_readlane_b32 s98, v138, 63
	v_readlane_b32 s99, v137, 63
	s_nop 1
	v_mov_b32_e32 v140, s99
	v_fma_f32 v141, -v140, v140, s98
	v_max_f32_e32 v141, 0, v141
	v_add_f32_e32 v141, 0x358637bd, v141
	v_mul_f32_e32 v142, 0x4b800000, v141
	v_cmp_gt_f32_e64 s[42:43], s58, v141
	s_nop 1
	v_cndmask_b32_e64 v141, v141, v142, s[42:43]
	v_rsq_f32_e32 v141, v141
	s_nop 0
	v_mul_f32_e32 v142, 0x45800000, v141
	v_cndmask_b32_e64 v141, v141, v142, s[42:43]
	v_mul_f32_e64 v139, -v140, v141
	s_and_saveexec_b64 s[16:17], s[40:41]
	s_cbranch_execz .LBB0_765
	v_lshl_add_u64 v[154:155], s[12:13], 0, v[86:87]
	global_store_dwordx2 v[154:155], v[140:141], off
.LBB0_765:
	s_or_b64 exec, exec, s[16:17]
	v_fma_f32 v121, v121, v141, v139
	v_fma_f32 v122, v122, v141, v139
	v_fma_f32 v123, v123, v141, v139
	v_fma_f32 v124, v124, v141, v139
	v_fma_f32 v125, v125, v141, v139
	v_fma_f32 v126, v126, v141, v139
	v_fma_f32 v127, v127, v141, v139
	v_fma_f32 v128, v128, v141, v139
	v_fma_f32 v129, v129, v141, v139
	v_fma_f32 v130, v130, v141, v139
	v_fma_f32 v131, v131, v141, v139
	v_fma_f32 v132, v132, v141, v139
	v_fma_f32 v133, v133, v141, v139
	v_fma_f32 v134, v134, v141, v139
	v_fma_f32 v135, v135, v141, v139
	v_fma_f32 v136, v136, v141, v139
	v_fma_f32 v121, v6, v121, v14
	v_fma_f32 v122, v7, v122, v15
	v_fma_f32 v123, v8, v123, v16
	v_fma_f32 v124, v9, v124, v17
	v_fma_f32 v125, v2, v125, v10
	v_fma_f32 v126, v3, v126, v11
	v_fma_f32 v127, v4, v127, v12
	v_fma_f32 v128, v5, v128, v13
	v_fma_f32 v129, v22, v129, v30
	v_fma_f32 v130, v23, v130, v31
	v_fma_f32 v131, v24, v131, v32
	v_fma_f32 v132, v25, v132, v33
	v_fma_f32 v133, v18, v133, v26
	v_fma_f32 v134, v19, v134, v27
	v_fma_f32 v135, v20, v135, v28
	v_fma_f32 v136, v21, v136, v29
	v_add_f32_e32 v137, v121, v122
	v_mul_f32_e32 v138, v121, v121
	v_fmac_f32_e32 v138, v122, v122
	v_add_f32_e32 v137, v137, v123
	v_fmac_f32_e32 v138, v123, v123
	v_add_f32_e32 v137, v137, v124
	v_fmac_f32_e32 v138, v124, v124
	v_add_f32_e32 v137, v137, v125
	v_fmac_f32_e32 v138, v125, v125
	v_add_f32_e32 v137, v137, v126
	v_fmac_f32_e32 v138, v126, v126
	v_add_f32_e32 v137, v137, v127
	v_fmac_f32_e32 v138, v127, v127
	v_add_f32_e32 v137, v137, v128
	v_fmac_f32_e32 v138, v128, v128
	v_add_f32_e32 v137, v137, v129
	v_fmac_f32_e32 v138, v129, v129
	v_add_f32_e32 v137, v137, v130
	v_fmac_f32_e32 v138, v130, v130
	v_add_f32_e32 v137, v137, v131
	v_fmac_f32_e32 v138, v131, v131
	v_add_f32_e32 v137, v137, v132
	v_fmac_f32_e32 v138, v132, v132
	v_add_f32_e32 v137, v137, v133
	v_fmac_f32_e32 v138, v133, v133
	v_add_f32_e32 v137, v137, v134
	v_fmac_f32_e32 v138, v134, v134
	v_add_f32_e32 v137, v137, v135
	v_fmac_f32_e32 v138, v135, v135
	v_add_f32_e32 v137, v137, v136
	v_fmac_f32_e32 v138, v136, v136
	s_nop 1
	v_add_f32_dpp v138, v138, v138 quad_perm:[1,0,3,2] row_mask:0xf bank_mask:0xf
	v_add_f32_dpp v137, v137, v137 quad_perm:[1,0,3,2] row_mask:0xf bank_mask:0xf
	s_nop 0
	v_add_f32_dpp v138, v138, v138 quad_perm:[2,3,0,1] row_mask:0xf bank_mask:0xf
	v_add_f32_dpp v137, v137, v137 quad_perm:[2,3,0,1] row_mask:0xf bank_mask:0xf
	s_nop 0
	v_add_f32_dpp v138, v138, v138 row_half_mirror row_mask:0xf bank_mask:0xf
	v_add_f32_dpp v137, v137, v137 row_half_mirror row_mask:0xf bank_mask:0xf
	s_nop 0
	v_add_f32_dpp v138, v138, v138 row_mirror row_mask:0xf bank_mask:0xf
	v_add_f32_dpp v137, v137, v137 row_mirror row_mask:0xf bank_mask:0xf
	s_nop 0
	v_add_f32_dpp v138, v138, v138 row_bcast:15 row_mask:0xa bank_mask:0xf
	v_add_f32_dpp v137, v137, v137 row_bcast:15 row_mask:0xa bank_mask:0xf
	s_nop 0
	v_add_f32_dpp v138, v138, v138 row_bcast:31 row_mask:0xc bank_mask:0xf
	v_add_f32_dpp v137, v137, v137 row_bcast:31 row_mask:0xc bank_mask:0xf
	s_nop 0
	s_mov_b32 s0, 0x3a800000
	v_mul_f32_e32 v138, s0, v138
	v_mul_f32_e32 v137, s0, v137
	s_nop 0
	v_readlane_b32 s98, v138, 63
	v_readlane_b32 s99, v137, 63
	v_add_u32_e32 v0, 0xfffff000, v92
	v_lshrrev_b32_e32 v0, 11, v0
	v_add_u32_e32 v0, 1, v0
	v_cmp_lt_i32_e64 s[42:43], s29, v92
	v_cndmask_b32_e64 v92, 0, v0, s[42:43]
	v_cmp_ne_u32_e64 s[42:43], v92, v117
	s_and_saveexec_b64 s[16:17], s[42:43]
	s_cbranch_execz .LBB0_760
	v_mul_u32_u24_e32 v0, 0x1800, v92
	v_lshlrev_b64 v[42:43], 2, v[0:1]
	v_lshl_add_u64 v[44:45], v[82:83], 0, v[42:43]
	v_lshl_add_u64 v[62:63], v[84:85], 0, v[42:43]
	global_load_dwordx4 v[54:57], v[44:45], off
	global_load_dwordx4 v[58:61], v[44:45], off offset:16
	global_load_dwordx4 v[70:73], v[44:45], off offset:2064
	global_load_dwordx4 v[66:69], v[44:45], off offset:2048
	s_nop 0
	global_load_dwordx4 v[42:45], v[62:63], off offset:16
	global_load_dwordx4 v[46:49], v[62:63], off
	global_load_dwordx4 v[50:53], v[62:63], off offset:2064
	s_nop 0
	global_load_dwordx4 v[62:65], v[62:63], off offset:2048
	v_mov_b32_e32 v117, v92
	s_waitcnt vmcnt(7)
	v_add_f32_e32 v56, 1.0, v56
	v_add_f32_e32 v57, 1.0, v57
	v_add_f32_e32 v54, 1.0, v54
	v_add_f32_e32 v55, 1.0, v55
	s_waitcnt vmcnt(6)
	v_add_f32_e32 v60, 1.0, v60
	v_add_f32_e32 v61, 1.0, v61
	v_add_f32_e32 v58, 1.0, v58
	v_add_f32_e32 v59, 1.0, v59
	s_waitcnt vmcnt(4)
	v_add_f32_e32 v68, 1.0, v68
	v_add_f32_e32 v69, 1.0, v69
	v_add_f32_e32 v66, 1.0, v66
	v_add_f32_e32 v67, 1.0, v67
	v_add_f32_e32 v72, 1.0, v72
	v_add_f32_e32 v73, 1.0, v73
	v_add_f32_e32 v70, 1.0, v70
	v_add_f32_e32 v71, 1.0, v71
	s_branch .LBB0_760
